# GQA attention loop: K/V tiles staged HBM->LDS by global_load_lds (swizzle on per-lane source offsets), K issued at top of half, V after barrier 1, one counted vmcnt(2); replaces global_load+ds_write_b
# speedup vs baseline: 1.0029x; 1.0025x over previous
; __device__ __forceinline__ int v_st(int k, int c) { const int kk = (k & ~0xC) | ((k & 4) << 1) | ((k & 8) >> 1); return ((kk >> 3) * 4 + (c >> 5)) * 512 + ((kk & 7) * 32 + (c & 31)) * 2; }
; __device__ __forceinline__ int v_rd_base(int lane) { return ((lane & 3) << 3) | (((lane >> 2) & 3) << 6) | (((lane >> 4) & 1) << 5) | (((lane >> 5) & 1) << 8); }
; template <int OFF> __device__ __forceinline__ s16x4 tr_read(int vb) {
;   s16x4 r; asm volatile("ds_read_b64_tr_b16 %0, %1 offset:%2" : "=&v"(r) : "v"(vb), "i"(OFF) : "memory"); return r;
; }
; template <int D0> __device__ __forceinline__ void pv_one(f32x16& od, int vb, bf16x8 pa0, bf16x8 pa1, bf16x8 pa2, bf16x8 pa3) {
;   const s16x4 l0 = tr_read<v_rd_off(D0, 0, 0)>(vb), h0 = tr_read<v_rd_off(D0, 0, 1)>(vb), l1 = tr_read<v_rd_off(D0, 1, 0)>(vb), h1 = tr_read<v_rd_off(D0, 1, 1)>(vb);
;   const s16x4 l2 = tr_read<v_rd_off(D0, 2, 0)>(vb), h2 = tr_read<v_rd_off(D0, 2, 1)>(vb), l3 = tr_read<v_rd_off(D0, 3, 0)>(vb), h3 = tr_read<v_rd_off(D0, 3, 1)>(vb);
;   asm volatile("s_waitcnt lgkmcnt(0)" ::: "memory"); SBAR();
;     ...
;   od = __builtin_amdgcn_mfma_f32_32x32x16_bf16(pa0, PK(l0, h0), od, 0, 0, 0);
;   od = __builtin_amdgcn_mfma_f32_32x32x16_bf16(pa1, PK(l1, h1), od, 0, 0, 0);
;   od = __builtin_amdgcn_mfma_f32_32x32x16_bf16(pa2, PK(l2, h2), od, 0, 0, 0);
;   od = __builtin_amdgcn_mfma_f32_32x32x16_bf16(pa3, PK(l3, h3), od, 0, 0, 0);
;     ...
; }
; __device__ __forceinline__ void pv_d0(f32x16* o, int vb, bf16x8 pa0, bf16x8 pa1, bf16x8 pa2, bf16x8 pa3) {
;   pv_one<0>(o[0], vb, pa0, pa1, pa2, pa3); pv_one<1>(o[1], vb, pa0, pa1, pa2, pa3); pv_one<2>(o[2], vb, pa0, pa1, pa2, pa3); pv_one<3>(o[3], vb, pa0, pa1, pa2, pa3);
; }
; template <int DK, int LDQ, int LDK, int LDV, int LDO, int SDEPTH, int NPARK>
; __device__ __forceinline__ void body(const bf16_t* __restrict__ Qb, const bf16_t* __restrict__ Kh, const bf16_t* __restrict__ Vh, bf16_t* __restrict__ Ob, int seq, char* lds, int tid, int wid) {
;   constexpr int SHM_K = KVBLK * DK * 2, ND0 = DK / 16;
;   const int lane = tid & 63, r32 = lane & 31, hi = lane >> 5;
;   char* V_lds = lds; char* K_lds = lds + 2 * SHM_V;
;   float* ws = (float*)(lds + 2 * SHM_V + 2 * SHM_K) + wid * 64; float* li_l = ws; float* al_l = ws + 32;
;   float m_reg = -1e30f, l_reg = 0; f32x16 o[4] = {}; bf16x8 qr[ND0 - NPARK];
;   const bf16_t* Qw = Qb + (long)(wid * QBLK + r32) * LDQ + hi * 8;
.LBB0_916:
	s_or_b64 exec, exec, s[42:43]
	s_mov_b64 s[4:5], s[96:97]
	s_waitcnt lgkmcnt(0)
	s_barrier
	v_mbcnt_lo_u32_b32 v244, -1, 0
	v_mbcnt_hi_u32_b32 v244, -1, v244
	s_lshl_b32 s52, s94, 11
	s_lshl_b32 s53, s94, 3
	v_lshrrev_b32_e32 v245, 4, v244
	v_add_u32_e32 v245, s53, v245
	v_and_b32_e32 v246, 15, v244
	v_lshrrev_b32_e32 v247, 4, v244
	v_xor_b32_e32 v246, v246, v247
	v_lshlrev_b32_e32 v246, 4, v246
	v_xor_b32_e32 v247, 64, v246
	v_lshl_add_u32 v246, v245, 9, v246
	v_add_u32_e32 v245, 4, v245
	v_lshl_add_u32 v247, v245, 9, v247
	v_and_b32_e32 v245, 31, v244
	v_lshrrev_b32_e32 v245, 2, v245
	v_add_u32_e32 v245, s53, v245
	v_and_b32_e32 v248, 4, v245
	v_and_b32_e32 v249, 8, v245
	v_and_b32_e32 v245, 0xfffffff3, v245
	v_lshl_or_b32 v245, v248, 1, v245
	v_lshrrev_b32_e32 v249, 1, v249
	v_or_b32_e32 v245, v245, v249
	v_lshrrev_b32_e32 v248, 5, v244
	v_lshlrev_b32_e32 v248, 6, v248
	v_and_b32_e32 v249, 3, v244
	v_lshl_or_b32 v248, v249, 4, v248
	v_lshl_add_u32 v244, v245, 9, v248
	v_add_u32_e32 v245, 0x80, v244
	s_load_dwordx2 s[24:25], s[4:5], 0xb8
	v_readlane_b32 s4, v254, 45
	v_readlane_b32 s5, v254, 46
	s_and_b64 s[4:5], s[4:5], exec
	s_movk_i32 s2, 0x220
	s_cselect_b32 s4, s2, 0x200
	s_waitcnt lgkmcnt(0)
	s_add_u32 s30, s24, 0x23fef000
	s_addc_u32 s31, s25, 0
	s_mov_b32 s2, s94
	s_cmp_ge_i32 s92, s4
	v_mbcnt_lo_u32_b32 v0, -1, 0
	v_mbcnt_hi_u32_b32 v0, -1, v0
	s_nop 0
	v_lshl_add_u32 v178, s2, 6, v0
	s_cbranch_scc1 .LBB0_940
	s_add_u32 s5, s24, 0x19e6f000
	s_addc_u32 s33, s25, 0
	s_add_u32 s34, s24, 0x1c06f000
	s_addc_u32 s35, s25, 0
	s_add_u32 s36, s24, 0x1c8ef000
	s_addc_u32 s37, s25, 0
	s_mov_b32 s42, s92
	s_branch .LBB0_919

; __device__ __forceinline__ void finishSM(f32x16& p0, f32x16& p1, float alpha, float& l_reg, bf16x8& pa0, bf16x8& pa1, bf16x8& pa2, bf16x8& pa3) {
; #pragma unroll
;   for (int r = 0; r < 16; ++r) p1[r] = __builtin_amdgcn_exp2f(p1[r]);
;   float ps = 0;
; #pragma unroll
;   for (int r = 0; r < 16; ++r) ps += p0[r];
; #pragma unroll
;   for (int r = 0; r < 16; ++r) ps += p1[r];
;   { auto rr = __builtin_amdgcn_permlane32_swap(__float_as_uint(ps), __float_as_uint(ps), false, false);
;     ps = __uint_as_float(rr[0]) + __uint_as_float(rr[1]); }
;   l_reg = l_reg * alpha + ps;
;     ...
;   PK4(p0, 0, pa0); PK4(p0, 8, pa1); PK4(p1, 0, pa2); PK4(p1, 8, pa3);
;     ...
; }
; template <int DK, int NPARK>
; __device__ __forceinline__ void qkt(f32x16& p0, f32x16& p1, const char* Ks, const bf16x8* qr, const char* qpark, int r32, int hi) {
;   p0 = f32x16{}; p1 = f32x16{};
; #pragma unroll
;   for (int d0 = 0; d0 < DK / 16; ++d0) { const int cb = (d0 * 16 + hi * 8) * 2;
;     bf16x8 b0 = *reinterpret_cast<const bf16x8*>(Ks + kswz<DK>(r32, cb));
;     bf16x8 b1 = *reinterpret_cast<const bf16x8*>(Ks + kswz<DK>(32 + r32, cb));
;     bf16x8 q;
;     if constexpr (NPARK > 0) { if (d0 >= DK / 16 - NPARK) q = *reinterpret_cast<const bf16x8*>(qpark + (d0 - (DK / 16 - NPARK)) * 1024); else q = qr[d0]; } else q = qr[d0];
;     p0 = __builtin_amdgcn_mfma_f32_32x32x16_bf16(b0, q, p0, 0, 0, 0);
;     p1 = __builtin_amdgcn_mfma_f32_32x32x16_bf16(b1, q, p1, 0, 0, 0); }
; }
.LBB0_924:
	s_add_u32 s48, s10, s67
	s_addc_u32 s49, s11, 0
	s_add_u32 m0, s52, 0x8000
	s_nop 0
	global_load_lds_dwordx4 v246, s[48:49]
	s_add_u32 m0, s52, 0x8400
	s_nop 0
	global_load_lds_dwordx4 v247, s[48:49]
	ds_read_b128 v[64:67], v161 offset:49152
	ds_read_b128 v[68:71], v161 offset:57344
	ds_read_b128 v[194:197], v170 offset:49152
	ds_read_b128 v[198:201], v170 offset:57344
	v_add_f32_e32 v144, v187, v145
	s_waitcnt lgkmcnt(3)
	v_mfma_f32_32x32x16_bf16 v[80:95], v[64:67], v[112:115], 0
	v_add_f32_e32 v144, v146, v144
	v_add_f32_e32 v144, v188, v144
	v_add_f32_e32 v144, v186, v144
	v_add_f32_e32 v144, v189, v144
	v_add_f32_e32 v144, v147, v144
	v_add_f32_e32 v144, v185, v144
	v_add_f32_e32 v144, v157, v144
	s_waitcnt lgkmcnt(2)
	v_mfma_f32_32x32x16_bf16 v[64:79], v[68:71], v[112:115], 0
	v_add_f32_e32 v144, v181, v144
	v_add_f32_e32 v144, v179, v144
	v_add_f32_e32 v144, v182, v144
	v_exp_f32_e32 v142, v142
	v_add_f32_e32 v144, v154, v144
	v_exp_f32_e32 v143, v143
	v_add_f32_e32 v144, v155, v144
	s_waitcnt lgkmcnt(1)
	v_mfma_f32_32x32x16_bf16 v[80:95], v[194:197], v[108:111], v[80:95]
	v_exp_f32_e32 v140, v140
	v_add_f32_e32 v144, v156, v144
	v_exp_f32_e32 v141, v141
	v_add_f32_e32 v144, v180, v144
	v_exp_f32_e32 v136, v136
	v_add_f32_e32 v144, v142, v144
	v_exp_f32_e32 v137, v137
	s_waitcnt lgkmcnt(0)
	v_mfma_f32_32x32x16_bf16 v[64:79], v[198:201], v[108:111], v[64:79]
	ds_read_b128 v[194:197], v169 offset:49152
	ds_read_b128 v[198:201], v169 offset:57344
	v_add_f32_e32 v144, v143, v144
	v_exp_f32_e32 v132, v132
	v_add_f32_e32 v144, v140, v144
	v_exp_f32_e32 v133, v133
	v_add_f32_e32 v144, v141, v144
	v_exp_f32_e32 v130, v130
	s_waitcnt lgkmcnt(1)
	v_mfma_f32_32x32x16_bf16 v[80:95], v[194:197], v[120:123], v[80:95]
	v_add_f32_e32 v144, v136, v144
	v_exp_f32_e32 v131, v131
	v_add_f32_e32 v144, v137, v144
	v_exp_f32_e32 v138, v138
	v_add_f32_e32 v144, v132, v144
	v_exp_f32_e32 v139, v139
	v_add_f32_e32 v144, v133, v144
	s_waitcnt lgkmcnt(0)
	v_mfma_f32_32x32x16_bf16 v[64:79], v[198:201], v[120:123], v[64:79]
	ds_read_b128 v[194:197], v168 offset:49152
	ds_read_b128 v[198:201], v168 offset:57344
	v_exp_f32_e32 v134, v134
	v_add_f32_e32 v144, v130, v144
	v_exp_f32_e32 v135, v135
	v_add_f32_e32 v144, v131, v144
	v_exp_f32_e32 v128, v128
	v_add_f32_e32 v144, v138, v144
	s_waitcnt lgkmcnt(1)
	v_mfma_f32_32x32x16_bf16 v[80:95], v[194:197], v[124:127], v[80:95]
	v_exp_f32_e32 v129, v129
	v_add_f32_e32 v144, v139, v144
	v_add_f32_e32 v144, v134, v144
	v_add_f32_e32 v144, v135, v144
	v_add_f32_e32 v144, v128, v144
	v_add_f32_e32 v175, v129, v144
	v_mov_b32_e32 v176, v175
	s_waitcnt lgkmcnt(0)
	v_mfma_f32_32x32x16_bf16 v[64:79], v[198:201], v[124:127], v[64:79]
	ds_read_b128 v[194:197], v167 offset:49152
	ds_read_b128 v[198:201], v167 offset:57344
	v_permlane32_swap_b32_e32 v175, v176
	s_waitcnt lgkmcnt(1)
	v_mfma_f32_32x32x16_bf16 v[80:95], v[194:197], v[116:119], v[80:95]
	s_waitcnt lgkmcnt(0)
	v_mfma_f32_32x32x16_bf16 v[64:79], v[198:201], v[116:119], v[64:79]
	ds_read_b128 v[194:197], v166 offset:49152
	ds_read_b128 v[198:201], v166 offset:57344
	s_waitcnt lgkmcnt(1)
	v_mfma_f32_32x32x16_bf16 v[80:95], v[194:197], v[104:107], v[80:95]
	s_waitcnt lgkmcnt(0)
	v_mfma_f32_32x32x16_bf16 v[64:79], v[198:201], v[104:107], v[64:79]
	ds_read_b128 v[194:197], v172 offset:49152
	ds_read_b128 v[198:201], v172 offset:57344
	s_waitcnt lgkmcnt(1)
	v_mfma_f32_32x32x16_bf16 v[80:95], v[194:197], v[100:103], v[80:95]
	s_waitcnt lgkmcnt(0)
	v_mfma_f32_32x32x16_bf16 v[64:79], v[198:201], v[100:103], v[64:79]
	ds_read_b128 v[194:197], v171 offset:49152
	ds_read_b128 v[198:201], v171 offset:57344
	v_cvt_pk_bf16_f32 v144, v145, v187
	v_cvt_pk_bf16_f32 v145, v146, v188
	v_cvt_pk_bf16_f32 v146, v186, v189
	v_cvt_pk_bf16_f32 v147, v147, v185
	v_cvt_pk_bf16_f32 v184, v157, v181
	v_cvt_pk_bf16_f32 v185, v179, v182
	s_waitcnt lgkmcnt(1)
	v_mfma_f32_32x32x16_bf16 v[80:95], v[194:197], v[96:99], v[80:95]
	v_permlane32_swap_b32_e32 v144, v146
	v_cvt_pk_bf16_f32 v186, v154, v155
	v_cvt_pk_bf16_f32 v187, v156, v180
	v_cvt_pk_bf16_f32 v180, v142, v143
	v_cvt_pk_bf16_f32 v181, v140, v141
	v_cvt_pk_bf16_f32 v182, v136, v137
	s_waitcnt lgkmcnt(0)
	v_mfma_f32_32x32x16_bf16 v[64:79], v[198:201], v[96:99], v[64:79]
	v_cvt_pk_bf16_f32 v183, v132, v133
	v_cvt_pk_bf16_f32 v188, v130, v131
	v_cvt_pk_bf16_f32 v189, v138, v139
	v_cvt_pk_bf16_f32 v190, v134, v135
	v_cvt_pk_bf16_f32 v191, v128, v129
	v_permlane32_swap_b32_e32 v145, v147
	v_permlane32_swap_b32_e32 v184, v186
	v_permlane32_swap_b32_e32 v185, v187
	v_permlane32_swap_b32_e32 v180, v182
	v_permlane32_swap_b32_e32 v181, v183
	v_permlane32_swap_b32_e32 v188, v190
	v_permlane32_swap_b32_e32 v189, v191
	ds_read_b64_tr_b16 v[194:195], v160 offset:0
	ds_read_b64_tr_b16 v[196:197], v160 offset:0x800
	ds_read_b64_tr_b16 v[198:199], v160 offset:0x1000
	ds_read_b64_tr_b16 v[200:201], v160 offset:0x1800
	ds_read_b64_tr_b16 v[202:203], v160 offset:0x2000
	ds_read_b64_tr_b16 v[204:205], v160 offset:0x2800
	ds_read_b64_tr_b16 v[206:207], v160 offset:0x3000
	ds_read_b64_tr_b16 v[208:209], v160 offset:0x3800
	s_waitcnt lgkmcnt(0)
	v_mfma_f32_32x32x16_bf16 v[0:15], v[144:147], v[194:197], v[0:15]
	ds_read_b64_tr_b16 v[194:195], v160 offset:0x200
	ds_read_b64_tr_b16 v[196:197], v160 offset:0xa00
	v_mfma_f32_32x32x16_bf16 v[0:15], v[184:187], v[198:201], v[0:15]
	ds_read_b64_tr_b16 v[198:199], v160 offset:0x1200
	ds_read_b64_tr_b16 v[200:201], v160 offset:0x1a00
	v_mfma_f32_32x32x16_bf16 v[0:15], v[180:183], v[202:205], v[0:15]
	ds_read_b64_tr_b16 v[202:203], v160 offset:0x2200
	ds_read_b64_tr_b16 v[204:205], v160 offset:0x2a00
	v_mfma_f32_32x32x16_bf16 v[0:15], v[188:191], v[206:209], v[0:15]
	ds_read_b64_tr_b16 v[206:207], v160 offset:0x3200
	ds_read_b64_tr_b16 v[208:209], v160 offset:0x3a00
	s_waitcnt lgkmcnt(0)
; #define SBAR() __builtin_amdgcn_sched_barrier(0)
; template <int DK>
; __device__ __forceinline__ void partialSM(f32x16& p0, f32x16& p1, float& m_reg, float& mn, float& alpha) {
;   constexpr float SCALE = Cst<DK>::SCALE, C = SCALE * 1.4426950408889634f;
;   float pmax = p0[0];
; #pragma unroll
;   for (int r = 1; r < 16; ++r) pmax = fmaxf(pmax, p0[r]);
; #pragma unroll
;   for (int r = 0; r < 16; ++r) pmax = fmaxf(pmax, p1[r]);
;   { auto rr = __builtin_amdgcn_permlane32_swap(__float_as_uint(pmax), __float_as_uint(pmax), false, false);
;     pmax = fmaxf(__uint_as_float(rr[0]), __uint_as_float(rr[1])); }
;   if (__builtin_expect(__all(pmax - m_reg <= THR / SCALE), 1)) { mn = m_reg; alpha = 1.f; }
;   else { mn = fmaxf(m_reg, pmax); alpha = __builtin_amdgcn_exp2f((m_reg - mn) * C); m_reg = mn; }
; template <int D0> __device__ __forceinline__ void pv_one(f32x16& od, int vb, bf16x8 pa0, bf16x8 pa1, bf16x8 pa2, bf16x8 pa3) {
;   const s16x4 l0 = tr_read<v_rd_off(D0, 0, 0)>(vb), h0 = tr_read<v_rd_off(D0, 0, 1)>(vb), l1 = tr_read<v_rd_off(D0, 1, 0)>(vb), h1 = tr_read<v_rd_off(D0, 1, 1)>(vb);
;   const s16x4 l2 = tr_read<v_rd_off(D0, 2, 0)>(vb), h2 = tr_read<v_rd_off(D0, 2, 1)>(vb), l3 = tr_read<v_rd_off(D0, 3, 0)>(vb), h3 = tr_read<v_rd_off(D0, 3, 1)>(vb);
;   asm volatile("s_waitcnt lgkmcnt(0)" ::: "memory"); SBAR();
;     ...
;   od = __builtin_amdgcn_mfma_f32_32x32x16_bf16(pa0, PK(l0, h0), od, 0, 0, 0);
;   od = __builtin_amdgcn_mfma_f32_32x32x16_bf16(pa1, PK(l1, h1), od, 0, 0, 0);
;   od = __builtin_amdgcn_mfma_f32_32x32x16_bf16(pa2, PK(l2, h2), od, 0, 0, 0);
;   od = __builtin_amdgcn_mfma_f32_32x32x16_bf16(pa3, PK(l3, h3), od, 0, 0, 0);
;     ...
; }
; __device__ __forceinline__ void pv_d0(f32x16* o, int vb, bf16x8 pa0, bf16x8 pa1, bf16x8 pa2, bf16x8 pa3) {
;   pv_one<0>(o[0], vb, pa0, pa1, pa2, pa3); pv_one<1>(o[1], vb, pa0, pa1, pa2, pa3); pv_one<2>(o[2], vb, pa0, pa1, pa2, pa3); pv_one<3>(o[3], vb, pa0, pa1, pa2, pa3);
	v_mfma_f32_32x32x16_bf16 v[48:63], v[144:147], v[194:197], v[48:63]
	ds_read_b64_tr_b16 v[194:195], v160 offset:0x400
	ds_read_b64_tr_b16 v[196:197], v160 offset:0xc00
	v_mfma_f32_32x32x16_bf16 v[48:63], v[184:187], v[198:201], v[48:63]
	ds_read_b64_tr_b16 v[198:199], v160 offset:0x1400
	ds_read_b64_tr_b16 v[200:201], v160 offset:0x1c00
	v_mfma_f32_32x32x16_bf16 v[48:63], v[180:183], v[202:205], v[48:63]
	ds_read_b64_tr_b16 v[202:203], v160 offset:0x2400
	ds_read_b64_tr_b16 v[204:205], v160 offset:0x2c00
	v_mfma_f32_32x32x16_bf16 v[48:63], v[188:191], v[206:209], v[48:63]
	ds_read_b64_tr_b16 v[206:207], v160 offset:0x3400
	ds_read_b64_tr_b16 v[208:209], v160 offset:0x3c00
	s_waitcnt lgkmcnt(0)
	v_mfma_f32_32x32x16_bf16 v[32:47], v[144:147], v[194:197], v[32:47]
	ds_read_b64_tr_b16 v[194:195], v160 offset:0x600
	ds_read_b64_tr_b16 v[196:197], v160 offset:0xe00
	v_mfma_f32_32x32x16_bf16 v[32:47], v[184:187], v[198:201], v[32:47]
	ds_read_b64_tr_b16 v[198:199], v160 offset:0x1600
	ds_read_b64_tr_b16 v[200:201], v160 offset:0x1e00
	v_mfma_f32_32x32x16_bf16 v[32:47], v[180:183], v[202:205], v[32:47]
	ds_read_b64_tr_b16 v[202:203], v160 offset:0x2600
	ds_read_b64_tr_b16 v[204:205], v160 offset:0x2e00
	v_mfma_f32_32x32x16_bf16 v[32:47], v[188:191], v[206:209], v[32:47]
	ds_read_b64_tr_b16 v[206:207], v160 offset:0x3600
	ds_read_b64_tr_b16 v[208:209], v160 offset:0x3e00
	s_waitcnt lgkmcnt(0)
	v_mfma_f32_32x32x16_bf16 v[16:31], v[144:147], v[194:197], v[16:31]
	v_max_f32_e32 v144, v80, v81
	v_max3_f32 v144, v144, v82, v83
	v_max3_f32 v144, v144, v84, v85
	v_max3_f32 v144, v144, v86, v87
	v_max3_f32 v144, v144, v88, v89
	v_max3_f32 v144, v144, v90, v91
	v_max3_f32 v144, v144, v92, v93
	v_mfma_f32_32x32x16_bf16 v[16:31], v[184:187], v[198:201], v[16:31]
	v_max3_f32 v144, v144, v94, v95
	v_max3_f32 v144, v144, v64, v65
	v_max3_f32 v144, v144, v66, v67
	v_max3_f32 v144, v144, v68, v69
	v_max3_f32 v144, v144, v70, v71
	v_max3_f32 v144, v144, v72, v73
	v_max3_f32 v144, v144, v74, v75
	v_max3_f32 v144, v144, v76, v77
	v_mfma_f32_32x32x16_bf16 v[16:31], v[180:183], v[202:205], v[16:31]
	v_max3_f32 v144, v144, v78, v79
	v_mov_b32_e32 v145, v144
	s_nop 1
	v_permlane32_swap_b32_e32 v144, v145
	v_max_f32_e32 v144, v144, v145
	v_sub_f32_e32 v145, v144, v174
	v_cmp_ge_f32_e32 vcc, s1, v145
	v_max_f32_e32 v144, v174, v144
	v_mfma_f32_32x32x16_bf16 v[16:31], v[188:191], v[206:209], v[16:31]
	v_sub_f32_e32 v145, v174, v144
	v_mul_f32_e32 v145, 0x3e0293ee, v145
	v_exp_f32_e32 v145, v145
	s_cmp_eq_u64 vcc, exec
	s_cselect_b64 s[8:9], -1, 0
	s_barrier
	v_cndmask_b32_e64 v177, v145, 1.0, s[8:9]
	v_cmp_gt_f32_e32 vcc, 1.0, v177
	s_add_u32 s48, s10, s0
	s_addc_u32 s49, s11, 0
	s_mov_b32 m0, s52
	s_nop 0
	global_load_lds_dwordx4 v244, s[48:49]
	s_add_u32 m0, s52, 0x400
	s_nop 0
	global_load_lds_dwordx4 v245, s[48:49]
	s_cbranch_vccz .LBB0_928
	s_and_saveexec_b64 s[12:13], s[6:7]
	ds_write_b32 v151, v177 offset:128
	s_or_b64 exec, exec, s[12:13]
	s_waitcnt lgkmcnt(0)
	v_add_u32_e32 v140, s95, v150
	ds_read_b128 v[128:131], v140 offset:224
	ds_read_b128 v[132:135], v140 offset:192
	ds_read_b128 v[136:139], v140 offset:160
	ds_read_b128 v[140:143], v140 offset:128
	s_waitcnt lgkmcnt(3)
	v_pk_mul_f32 v[12:13], v[12:13], v[128:129]
	s_waitcnt lgkmcnt(2)
	v_pk_mul_f32 v[8:9], v[8:9], v[132:133]
	s_waitcnt lgkmcnt(1)
	v_pk_mul_f32 v[4:5], v[4:5], v[136:137]
	v_pk_mul_f32 v[14:15], v[14:15], v[130:131]
	v_pk_mul_f32 v[10:11], v[10:11], v[134:135]
	v_pk_mul_f32 v[6:7], v[6:7], v[138:139]
	s_waitcnt lgkmcnt(0)
	v_pk_mul_f32 v[2:3], v[2:3], v[142:143]
	v_pk_mul_f32 v[0:1], v[0:1], v[140:141]
	v_pk_mul_f32 v[60:61], v[60:61], v[128:129]
	v_pk_mul_f32 v[56:57], v[56:57], v[132:133]
	v_pk_mul_f32 v[52:53], v[52:53], v[136:137]
	v_pk_mul_f32 v[62:63], v[62:63], v[130:131]
	v_pk_mul_f32 v[58:59], v[58:59], v[134:135]
	v_pk_mul_f32 v[54:55], v[54:55], v[138:139]
	v_pk_mul_f32 v[50:51], v[50:51], v[142:143]
	v_pk_mul_f32 v[48:49], v[48:49], v[140:141]
	v_pk_mul_f32 v[44:45], v[44:45], v[128:129]
	v_pk_mul_f32 v[40:41], v[40:41], v[132:133]
	v_pk_mul_f32 v[36:37], v[36:37], v[136:137]
	v_pk_mul_f32 v[46:47], v[46:47], v[130:131]
	v_pk_mul_f32 v[42:43], v[42:43], v[134:135]
	v_pk_mul_f32 v[38:39], v[38:39], v[138:139]
	v_pk_mul_f32 v[34:35], v[34:35], v[142:143]
	v_pk_mul_f32 v[32:33], v[32:33], v[140:141]
	v_pk_mul_f32 v[28:29], v[28:29], v[128:129]
	v_pk_mul_f32 v[24:25], v[24:25], v[132:133]
	v_pk_mul_f32 v[20:21], v[20:21], v[136:137]
	v_pk_mul_f32 v[30:31], v[30:31], v[130:131]
	v_pk_mul_f32 v[26:27], v[26:27], v[134:135]
	v_pk_mul_f32 v[22:23], v[22:23], v[138:139]
	v_pk_mul_f32 v[18:19], v[18:19], v[142:143]
	v_pk_mul_f32 v[16:17], v[16:17], v[140:141]
; template <int DK>
; __device__ __forceinline__ void partialSM(f32x16& p0, f32x16& p1, float& m_reg, float& mn, float& alpha) {
;     ...
;   float mnC = -mn * C;
; #pragma unroll
;   for (int r = 0; r < 16; ++r) p0[r] = fmaf(p0[r], C, mnC);
; #pragma unroll
;   for (int r = 0; r < 16; ++r) p1[r] = fmaf(p1[r], C, mnC);
; #pragma unroll
;   for (int r = 0; r < 16; ++r) p0[r] = __builtin_amdgcn_exp2f(p0[r]);
; }
; template <int DK, int NPARK>
; __device__ __forceinline__ void qkt(f32x16& p0, f32x16& p1, const char* Ks, const bf16x8* qr, const char* qpark, int r32, int hi) {
;   p0 = f32x16{}; p1 = f32x16{};
; #pragma unroll
;   for (int d0 = 0; d0 < DK / 16; ++d0) { const int cb = (d0 * 16 + hi * 8) * 2;
;     bf16x8 b0 = *reinterpret_cast<const bf16x8*>(Ks + kswz<DK>(r32, cb));
;     bf16x8 b1 = *reinterpret_cast<const bf16x8*>(Ks + kswz<DK>(32 + r32, cb));
;     bf16x8 q;
;     if constexpr (NPARK > 0) { if (d0 >= DK / 16 - NPARK) q = *reinterpret_cast<const bf16x8*>(qpark + (d0 - (DK / 16 - NPARK)) * 1024); else q = qr[d0]; } else q = qr[d0];
;     p0 = __builtin_amdgcn_mfma_f32_32x32x16_bf16(b0, q, p0, 0, 0, 0);
;     p1 = __builtin_amdgcn_mfma_f32_32x32x16_bf16(b1, q, p1, 0, 0, 0); }
; }
.LBB0_928:
	v_cndmask_b32_e64 v174, v144, v174, s[8:9]
	v_mul_f32_e32 v144, 0xbe0293ee, v174
	v_pk_fma_f32 v[80:81], v[80:81], s[76:77], v[144:145] op_sel_hi:[1,0,0]
	v_pk_fma_f32 v[82:83], v[82:83], s[76:77], v[144:145] op_sel_hi:[1,0,0]
	v_pk_fma_f32 v[84:85], v[84:85], s[76:77], v[144:145] op_sel_hi:[1,0,0]
	v_pk_fma_f32 v[86:87], v[86:87], s[76:77], v[144:145] op_sel_hi:[1,0,0]
	v_pk_fma_f32 v[88:89], v[88:89], s[76:77], v[144:145] op_sel_hi:[1,0,0]
	v_pk_fma_f32 v[90:91], v[90:91], s[76:77], v[144:145] op_sel_hi:[1,0,0]
	v_pk_fma_f32 v[92:93], v[92:93], s[76:77], v[144:145] op_sel_hi:[1,0,0]
	v_pk_fma_f32 v[94:95], v[94:95], s[76:77], v[144:145] op_sel_hi:[1,0,0]
	v_fmamk_f32 v184, v64, 0x3e0293ee, v144
	v_fmamk_f32 v185, v65, 0x3e0293ee, v144
	v_fmamk_f32 v186, v66, 0x3e0293ee, v144
	v_fmamk_f32 v187, v67, 0x3e0293ee, v144
	v_fmamk_f32 v188, v68, 0x3e0293ee, v144
	v_fmamk_f32 v146, v69, 0x3e0293ee, v144
	v_fmamk_f32 v147, v70, 0x3e0293ee, v144
	v_fmamk_f32 v179, v71, 0x3e0293ee, v144
	v_fmamk_f32 v180, v72, 0x3e0293ee, v144
	v_fmamk_f32 v181, v73, 0x3e0293ee, v144
	v_fmamk_f32 v182, v74, 0x3e0293ee, v144
	v_fmamk_f32 v183, v75, 0x3e0293ee, v144
	v_fmamk_f32 v145, v76, 0x3e0293ee, v144
	v_fmamk_f32 v189, v77, 0x3e0293ee, v144
	v_fmamk_f32 v190, v78, 0x3e0293ee, v144
	v_fmac_f32_e32 v144, 0x3e0293ee, v79
	v_exp_f32_e32 v141, v80
	v_exp_f32_e32 v143, v81
	v_exp_f32_e32 v139, v82
	v_exp_f32_e32 v142, v83
	v_exp_f32_e32 v138, v84
	v_exp_f32_e32 v140, v85
	v_exp_f32_e32 v136, v86
	v_exp_f32_e32 v137, v87
	v_exp_f32_e32 v133, v88
	v_exp_f32_e32 v135, v89
	v_exp_f32_e32 v132, v90
	v_exp_f32_e32 v134, v91
	v_exp_f32_e32 v129, v92
	v_exp_f32_e32 v131, v93
	v_exp_f32_e32 v128, v94
	v_exp_f32_e32 v130, v95
	s_waitcnt vmcnt(2)
	s_waitcnt lgkmcnt(0)
	s_barrier
	s_add_u32 s48, s10, s64
	s_addc_u32 s49, s11, 0
	s_add_u32 m0, s52, 0xc000
	s_nop 0
	global_load_lds_dwordx4 v246, s[48:49]
	s_add_u32 m0, s52, 0xc400
	s_nop 0
	global_load_lds_dwordx4 v247, s[48:49]
	ds_read_b128 v[64:67], v161 offset:32768
	ds_read_b128 v[68:71], v161 offset:40960
	ds_read_b128 v[194:197], v170 offset:32768
	ds_read_b128 v[198:201], v170 offset:40960
	v_exp_f32_e32 v203, v144
	s_waitcnt lgkmcnt(3)
	v_mfma_f32_32x32x16_bf16 v[80:95], v[64:67], v[112:115], 0
	v_add_f32_e32 v144, v143, v141
	v_add_f32_e32 v144, v139, v144
	v_add_f32_e32 v144, v142, v144
	v_add_f32_e32 v144, v138, v144
	v_add_f32_e32 v144, v140, v144
	v_add_f32_e32 v144, v136, v144
	v_add_f32_e32 v144, v137, v144
	s_waitcnt lgkmcnt(2)
	v_mfma_f32_32x32x16_bf16 v[64:79], v[68:71], v[112:115], 0
	v_add_f32_e32 v144, v133, v144
	v_add_f32_e32 v144, v135, v144
	v_add_f32_e32 v144, v132, v144
	v_add_f32_e32 v144, v134, v144
	v_exp_f32_e32 v191, v184
	v_add_f32_e32 v144, v129, v144
	v_exp_f32_e32 v185, v185
	s_waitcnt lgkmcnt(1)
	v_mfma_f32_32x32x16_bf16 v[80:95], v[194:197], v[108:111], v[80:95]
	v_add_f32_e32 v144, v131, v144
	v_add_f32_e32 v144, v128, v144
	v_add_f32_e32 v144, v130, v144
	v_add_f32_e32 v144, v191, v144
	v_add_f32_e32 v144, v185, v144
	v_exp_f32_e32 v179, v179
	v_exp_f32_e32 v180, v180
	s_waitcnt lgkmcnt(0)
	v_mfma_f32_32x32x16_bf16 v[64:79], v[198:201], v[108:111], v[64:79]
	ds_read_b128 v[194:197], v169 offset:32768
	ds_read_b128 v[198:201], v169 offset:40960
	v_exp_f32_e32 v181, v181
	v_exp_f32_e32 v182, v182
	v_exp_f32_e32 v202, v189
	v_exp_f32_e32 v190, v190
	s_waitcnt lgkmcnt(1)
	v_mfma_f32_32x32x16_bf16 v[80:95], v[194:197], v[120:123], v[80:95]
	s_waitcnt lgkmcnt(0)
	v_mfma_f32_32x32x16_bf16 v[64:79], v[198:201], v[120:123], v[64:79]
	ds_read_b128 v[194:197], v168 offset:32768
	ds_read_b128 v[198:201], v168 offset:40960
	s_waitcnt lgkmcnt(1)
	v_mfma_f32_32x32x16_bf16 v[80:95], v[194:197], v[124:127], v[80:95]
	s_waitcnt lgkmcnt(0)
	v_mfma_f32_32x32x16_bf16 v[64:79], v[198:201], v[124:127], v[64:79]
	ds_read_b128 v[194:197], v167 offset:32768
	ds_read_b128 v[198:201], v167 offset:40960
	s_waitcnt lgkmcnt(1)
	v_mfma_f32_32x32x16_bf16 v[80:95], v[194:197], v[116:119], v[80:95]
	s_waitcnt lgkmcnt(0)
	v_mfma_f32_32x32x16_bf16 v[64:79], v[198:201], v[116:119], v[64:79]
	ds_read_b128 v[194:197], v166 offset:32768
	ds_read_b128 v[198:201], v166 offset:40960
	s_waitcnt lgkmcnt(1)
	v_mfma_f32_32x32x16_bf16 v[80:95], v[194:197], v[104:107], v[80:95]
	s_waitcnt lgkmcnt(0)
	v_mfma_f32_32x32x16_bf16 v[64:79], v[198:201], v[104:107], v[64:79]
	ds_read_b128 v[194:197], v172 offset:32768
	ds_read_b128 v[198:201], v172 offset:40960
	s_waitcnt lgkmcnt(1)
	v_mfma_f32_32x32x16_bf16 v[80:95], v[194:197], v[100:103], v[80:95]
	s_waitcnt lgkmcnt(0)
	v_mfma_f32_32x32x16_bf16 v[64:79], v[198:201], v[100:103], v[64:79]
	ds_read_b128 v[194:197], v171 offset:32768
	ds_read_b128 v[198:201], v171 offset:40960
	s_waitcnt lgkmcnt(1)
	v_mfma_f32_32x32x16_bf16 v[80:95], v[194:197], v[96:99], v[80:95]
	v_exp_f32_e32 v195, v186
	v_exp_f32_e32 v196, v187
	v_exp_f32_e32 v197, v188
	v_add_f32_e32 v144, v195, v144
	v_add_f32_e32 v144, v196, v144
	v_add_f32_e32 v144, v197, v144
	s_waitcnt lgkmcnt(0)
; __device__ __forceinline__ void finishSM(f32x16& p0, f32x16& p1, float alpha, float& l_reg, bf16x8& pa0, bf16x8& pa1, bf16x8& pa2, bf16x8& pa3) {
; #pragma unroll
;   for (int r = 0; r < 16; ++r) p1[r] = __builtin_amdgcn_exp2f(p1[r]);
;   float ps = 0;
; #pragma unroll
;   for (int r = 0; r < 16; ++r) ps += p0[r];
; #pragma unroll
;   for (int r = 0; r < 16; ++r) ps += p1[r];
;   { auto rr = __builtin_amdgcn_permlane32_swap(__float_as_uint(ps), __float_as_uint(ps), false, false);
;     ps = __uint_as_float(rr[0]) + __uint_as_float(rr[1]); }
;   l_reg = l_reg * alpha + ps;
;     ...
;   PK4(p0, 0, pa0); PK4(p0, 8, pa1); PK4(p1, 0, pa2); PK4(p1, 8, pa3);
;     ...
; }
; template <int DK, int NPARK>
; __device__ __forceinline__ void qkt(f32x16& p0, f32x16& p1, const char* Ks, const bf16x8* qr, const char* qpark, int r32, int hi) {
;   p0 = f32x16{}; p1 = f32x16{};
; #pragma unroll
;   for (int d0 = 0; d0 < DK / 16; ++d0) { const int cb = (d0 * 16 + hi * 8) * 2;
;     bf16x8 b0 = *reinterpret_cast<const bf16x8*>(Ks + kswz<DK>(r32, cb));
;     bf16x8 b1 = *reinterpret_cast<const bf16x8*>(Ks + kswz<DK>(32 + r32, cb));
;     bf16x8 q;
;     if constexpr (NPARK > 0) { if (d0 >= DK / 16 - NPARK) q = *reinterpret_cast<const bf16x8*>(qpark + (d0 - (DK / 16 - NPARK)) * 1024); else q = qr[d0]; } else q = qr[d0];
;     p0 = __builtin_amdgcn_mfma_f32_32x32x16_bf16(b0, q, p0, 0, 0, 0);
;     p1 = __builtin_amdgcn_mfma_f32_32x32x16_bf16(b1, q, p1, 0, 0, 0); }
; }
; __device__ __forceinline__ int v_st(int k, int c) { const int kk = (k & ~0xC) | ((k & 4) << 1) | ((k & 8) >> 1); return ((kk >> 3) * 4 + (c >> 5)) * 512 + ((kk & 7) * 32 + (c & 31)) * 2; }
; __device__ __forceinline__ int v_rd_base(int lane) { return ((lane & 3) << 3) | (((lane >> 2) & 3) << 6) | (((lane >> 4) & 1) << 5) | (((lane >> 5) & 1) << 8); }
; template <int OFF> __device__ __forceinline__ s16x4 tr_read(int vb) {
;   s16x4 r; asm volatile("ds_read_b64_tr_b16 %0, %1 offset:%2" : "=&v"(r) : "v"(vb), "i"(OFF) : "memory"); return r;
; }
; template <int D0> __device__ __forceinline__ void pv_one(f32x16& od, int vb, bf16x8 pa0, bf16x8 pa1, bf16x8 pa2, bf16x8 pa3) {
;   const s16x4 l0 = tr_read<v_rd_off(D0, 0, 0)>(vb), h0 = tr_read<v_rd_off(D0, 0, 1)>(vb), l1 = tr_read<v_rd_off(D0, 1, 0)>(vb), h1 = tr_read<v_rd_off(D0, 1, 1)>(vb);
	v_mfma_f32_32x32x16_bf16 v[64:79], v[198:201], v[96:99], v[64:79]
	v_exp_f32_e32 v198, v146
	v_exp_f32_e32 v199, v147
	v_exp_f32_e32 v200, v183
	v_exp_f32_e32 v201, v145
	v_add_f32_e32 v144, v198, v144
	v_add_f32_e32 v144, v199, v144
	v_add_f32_e32 v144, v179, v144
	v_add_f32_e32 v144, v180, v144
	v_add_f32_e32 v144, v181, v144
	v_add_f32_e32 v144, v182, v144
	v_add_f32_e32 v144, v200, v144
	v_add_f32_e32 v144, v201, v144
	v_add_f32_e32 v144, v202, v144
	v_add_f32_e32 v144, v190, v144
	v_add_f32_e32 v183, v203, v144
	v_mov_b32_e32 v184, v183
	v_cvt_pk_bf16_f32 v144, v141, v143
	v_cvt_pk_bf16_f32 v145, v139, v142
	v_cvt_pk_bf16_f32 v146, v138, v140
	v_cvt_pk_bf16_f32 v147, v136, v137
	s_nop 1
	v_permlane32_swap_b32_e32 v183, v184
	v_permlane32_swap_b32_e32 v144, v146
	v_permlane32_swap_b32_e32 v145, v147
	v_cvt_pk_bf16_f32 v186, v133, v135
	v_cvt_pk_bf16_f32 v187, v132, v134
	v_cvt_pk_bf16_f32 v188, v129, v131
	v_cvt_pk_bf16_f32 v189, v128, v130
	v_cvt_pk_bf16_f32 v194, v191, v185
	v_cvt_pk_bf16_f32 v195, v195, v196
	v_cvt_pk_bf16_f32 v196, v197, v198
	v_cvt_pk_bf16_f32 v197, v199, v179
	v_cvt_pk_bf16_f32 v198, v180, v181
	v_cvt_pk_bf16_f32 v199, v182, v200
	v_cvt_pk_bf16_f32 v200, v201, v202
	v_cvt_pk_bf16_f32 v201, v190, v203
	s_nop 0
	v_permlane32_swap_b32_e32 v186, v188
	v_permlane32_swap_b32_e32 v187, v189
	v_permlane32_swap_b32_e32 v194, v196
	v_permlane32_swap_b32_e32 v195, v197
	v_permlane32_swap_b32_e32 v198, v200
	v_permlane32_swap_b32_e32 v199, v201
	ds_read_b64_tr_b16 v[154:155], v159 offset:0
	ds_read_b64_tr_b16 v[156:157], v159 offset:0x800
	ds_read_b64_tr_b16 v[202:203], v159 offset:0x1000
	ds_read_b64_tr_b16 v[204:205], v159 offset:0x1800
	ds_read_b64_tr_b16 v[206:207], v159 offset:0x2000
	ds_read_b64_tr_b16 v[208:209], v159 offset:0x2800
	ds_read_b64_tr_b16 v[210:211], v159 offset:0x3000
	ds_read_b64_tr_b16 v[212:213], v159 offset:0x3800
	s_waitcnt lgkmcnt(0)
	v_mfma_f32_32x32x16_bf16 v[0:15], v[144:147], v[154:157], v[0:15]
	ds_read_b64_tr_b16 v[154:155], v159 offset:0x200
	ds_read_b64_tr_b16 v[156:157], v159 offset:0xa00
	v_mfma_f32_32x32x16_bf16 v[0:15], v[186:189], v[202:205], v[0:15]
	ds_read_b64_tr_b16 v[202:203], v159 offset:0x1200
	ds_read_b64_tr_b16 v[204:205], v159 offset:0x1a00
	v_mfma_f32_32x32x16_bf16 v[0:15], v[194:197], v[206:209], v[0:15]
	ds_read_b64_tr_b16 v[206:207], v159 offset:0x2200
	ds_read_b64_tr_b16 v[208:209], v159 offset:0x2a00
	v_mfma_f32_32x32x16_bf16 v[0:15], v[198:201], v[210:213], v[0:15]
	ds_read_b64_tr_b16 v[210:211], v159 offset:0x3200
	ds_read_b64_tr_b16 v[212:213], v159 offset:0x3a00
	s_waitcnt lgkmcnt(0)
	v_mfma_f32_32x32x16_bf16 v[48:63], v[144:147], v[154:157], v[48:63]
	ds_read_b64_tr_b16 v[154:155], v159 offset:0x400
	ds_read_b64_tr_b16 v[156:157], v159 offset:0xc00
	v_mfma_f32_32x32x16_bf16 v[48:63], v[186:189], v[202:205], v[48:63]
	ds_read_b64_tr_b16 v[202:203], v159 offset:0x1400
	ds_read_b64_tr_b16 v[204:205], v159 offset:0x1c00
	v_mfma_f32_32x32x16_bf16 v[48:63], v[194:197], v[206:209], v[48:63]
	ds_read_b64_tr_b16 v[206:207], v159 offset:0x2400
	ds_read_b64_tr_b16 v[208:209], v159 offset:0x2c00
	v_mfma_f32_32x32x16_bf16 v[48:63], v[198:201], v[210:213], v[48:63]
	ds_read_b64_tr_b16 v[210:211], v159 offset:0x3400
	ds_read_b64_tr_b16 v[212:213], v159 offset:0x3c00
	s_waitcnt lgkmcnt(0)
	v_mfma_f32_32x32x16_bf16 v[32:47], v[144:147], v[154:157], v[32:47]
	ds_read_b64_tr_b16 v[154:155], v159 offset:0x600
	ds_read_b64_tr_b16 v[156:157], v159 offset:0xe00
	v_mfma_f32_32x32x16_bf16 v[32:47], v[186:189], v[202:205], v[32:47]
	ds_read_b64_tr_b16 v[202:203], v159 offset:0x1600
	ds_read_b64_tr_b16 v[204:205], v159 offset:0x1e00
	v_mfma_f32_32x32x16_bf16 v[32:47], v[194:197], v[206:209], v[32:47]
	ds_read_b64_tr_b16 v[206:207], v159 offset:0x2600
	ds_read_b64_tr_b16 v[208:209], v159 offset:0x2e00
	v_mfma_f32_32x32x16_bf16 v[32:47], v[198:201], v[210:213], v[32:47]
	ds_read_b64_tr_b16 v[210:211], v159 offset:0x3600
	ds_read_b64_tr_b16 v[212:213], v159 offset:0x3e00
	s_waitcnt lgkmcnt(0)
	v_mfma_f32_32x32x16_bf16 v[16:31], v[144:147], v[154:157], v[16:31]
	v_max_f32_e32 v144, v80, v81
	v_max3_f32 v144, v144, v82, v83
	v_max3_f32 v144, v144, v84, v85
	v_max3_f32 v144, v144, v86, v87
	v_max3_f32 v144, v144, v88, v89
	v_max3_f32 v144, v144, v90, v91
	v_max3_f32 v144, v144, v92, v93
	v_mfma_f32_32x32x16_bf16 v[16:31], v[186:189], v[202:205], v[16:31]
	v_max3_f32 v144, v144, v94, v95
	v_max3_f32 v144, v144, v64, v65
	v_max3_f32 v144, v144, v66, v67
	v_max3_f32 v144, v144, v68, v69
	v_max3_f32 v144, v144, v70, v71
	v_max3_f32 v144, v144, v72, v73
	v_max3_f32 v144, v144, v74, v75
	v_max3_f32 v144, v144, v76, v77
	v_mfma_f32_32x32x16_bf16 v[16:31], v[194:197], v[206:209], v[16:31]
	v_max3_f32 v144, v144, v78, v79
	v_mov_b32_e32 v145, v144
	s_nop 1
	v_permlane32_swap_b32_e32 v144, v145
	v_max_f32_e32 v144, v144, v145
	v_sub_f32_e32 v145, v144, v174
	v_cmp_ge_f32_e32 vcc, s1, v145
	v_max_f32_e32 v145, v174, v144
	v_mfma_f32_32x32x16_bf16 v[16:31], v[198:201], v[210:213], v[16:31]
	v_sub_f32_e32 v144, v174, v145
	v_mul_f32_e32 v144, 0x3e0293ee, v144
	v_exp_f32_e32 v144, v144
	s_cmp_eq_u64 vcc, exec
	s_cselect_b64 s[8:9], -1, 0
	s_barrier
	v_cndmask_b32_e64 v144, v144, 1.0, s[8:9]
	v_cmp_gt_f32_e32 vcc, 1.0, v144
	s_add_u32 s48, s10, s61
	s_addc_u32 s49, s11, 0
	s_add_u32 m0, s52, 0x4000
	s_nop 0
	global_load_lds_dwordx4 v244, s[48:49]
	s_add_u32 m0, s52, 0x4400
	s_nop 0
	global_load_lds_dwordx4 v245, s[48:49]
	s_cbranch_vccz .LBB0_932
; #define SBAR() __builtin_amdgcn_sched_barrier(0)
; template <int DK>
; __device__ __forceinline__ void partialSM(f32x16& p0, f32x16& p1, float& m_reg, float& mn, float& alpha) {
;     ...
;   float mnC = -mn * C;
; #pragma unroll
;   for (int r = 0; r < 16; ++r) p0[r] = fmaf(p0[r], C, mnC);
; #pragma unroll
;   for (int r = 0; r < 16; ++r) p1[r] = fmaf(p1[r], C, mnC);
; #pragma unroll
;   for (int r = 0; r < 16; ++r) p0[r] = __builtin_amdgcn_exp2f(p0[r]);
; }
; template <int DK, int LDQ, int LDK, int LDV, int LDO, int SDEPTH, int NPARK>
; __device__ __forceinline__ void body(const bf16_t* __restrict__ Qb, const bf16_t* __restrict__ Kh, const bf16_t* __restrict__ Vh, bf16_t* __restrict__ Ob, int seq, char* lds, int tid, int wid) {
;     ...
;   SBAR(); qkt<DK, NPARK>(pB0, pB1, K_lds + SHM_K, qr, qpark, r32, hi);
;   finishSM(pA0, pA1, alA, l_reg, pa0, pa1, pa2, pa3); SBAR();
;   pv_d0(o, vb0, pa0, pa1, pa2, pa3); partialSM<DK>(pB0, pB1, m_reg, mnB, alB);
	s_and_saveexec_b64 s[12:13], s[6:7]
	ds_write_b32 v151, v144 offset:128
	s_or_b64 exec, exec, s[12:13]
	s_waitcnt lgkmcnt(0)
	v_add_u32_e32 v140, s95, v150
	ds_read_b128 v[128:131], v140 offset:224
	ds_read_b128 v[132:135], v140 offset:192
	ds_read_b128 v[136:139], v140 offset:160
	ds_read_b128 v[140:143], v140 offset:128
	s_waitcnt lgkmcnt(3)
	v_pk_mul_f32 v[12:13], v[12:13], v[128:129]
	s_waitcnt lgkmcnt(2)
	v_pk_mul_f32 v[8:9], v[8:9], v[132:133]
	s_waitcnt lgkmcnt(1)
	v_pk_mul_f32 v[4:5], v[4:5], v[136:137]
	v_pk_mul_f32 v[14:15], v[14:15], v[130:131]
	v_pk_mul_f32 v[10:11], v[10:11], v[134:135]
	v_pk_mul_f32 v[6:7], v[6:7], v[138:139]
	s_waitcnt lgkmcnt(0)
	v_pk_mul_f32 v[2:3], v[2:3], v[142:143]
	v_pk_mul_f32 v[0:1], v[0:1], v[140:141]
	v_pk_mul_f32 v[60:61], v[60:61], v[128:129]
	v_pk_mul_f32 v[56:57], v[56:57], v[132:133]
	v_pk_mul_f32 v[52:53], v[52:53], v[136:137]
	v_pk_mul_f32 v[62:63], v[62:63], v[130:131]
	v_pk_mul_f32 v[58:59], v[58:59], v[134:135]
	v_pk_mul_f32 v[54:55], v[54:55], v[138:139]
	v_pk_mul_f32 v[50:51], v[50:51], v[142:143]
	v_pk_mul_f32 v[48:49], v[48:49], v[140:141]
	v_pk_mul_f32 v[44:45], v[44:45], v[128:129]
	v_pk_mul_f32 v[40:41], v[40:41], v[132:133]
	v_pk_mul_f32 v[36:37], v[36:37], v[136:137]
	v_pk_mul_f32 v[46:47], v[46:47], v[130:131]
	v_pk_mul_f32 v[42:43], v[42:43], v[134:135]
	v_pk_mul_f32 v[38:39], v[38:39], v[138:139]
	v_pk_mul_f32 v[34:35], v[34:35], v[142:143]
	v_pk_mul_f32 v[32:33], v[32:33], v[140:141]
	v_pk_mul_f32 v[28:29], v[28:29], v[128:129]
	v_pk_mul_f32 v[24:25], v[24:25], v[132:133]
	v_pk_mul_f32 v[20:21], v[20:21], v[136:137]
	v_pk_mul_f32 v[30:31], v[30:31], v[130:131]
	v_pk_mul_f32 v[26:27], v[26:27], v[134:135]
	v_pk_mul_f32 v[22:23], v[22:23], v[138:139]
	v_pk_mul_f32 v[18:19], v[18:19], v[142:143]
	v_pk_mul_f32 v[16:17], v[16:17], v[140:141]
.LBB0_932:
	v_cndmask_b32_e64 v174, v145, v174, s[8:9]
	v_mul_f32_e32 v128, 0xbe0293ee, v174
	v_pk_fma_f32 v[80:81], v[80:81], s[76:77], v[128:129] op_sel_hi:[1,0,0]
	v_pk_fma_f32 v[82:83], v[82:83], s[76:77], v[128:129] op_sel_hi:[1,0,0]
	v_pk_fma_f32 v[84:85], v[84:85], s[76:77], v[128:129] op_sel_hi:[1,0,0]
	v_pk_fma_f32 v[86:87], v[86:87], s[76:77], v[128:129] op_sel_hi:[1,0,0]
	v_pk_fma_f32 v[88:89], v[88:89], s[76:77], v[128:129] op_sel_hi:[1,0,0]
	v_pk_fma_f32 v[90:91], v[90:91], s[76:77], v[128:129] op_sel_hi:[1,0,0]
	v_pk_fma_f32 v[92:93], v[92:93], s[76:77], v[128:129] op_sel_hi:[1,0,0]
	v_pk_fma_f32 v[94:95], v[94:95], s[76:77], v[128:129] op_sel_hi:[1,0,0]
	v_exp_f32_e32 v145, v80
	v_exp_f32_e32 v187, v81
	v_exp_f32_e32 v146, v82
	v_exp_f32_e32 v188, v83
	v_exp_f32_e32 v186, v84
	v_exp_f32_e32 v189, v85
	v_exp_f32_e32 v147, v86
	v_exp_f32_e32 v185, v87
	v_exp_f32_e32 v157, v88
	v_exp_f32_e32 v181, v89
	v_exp_f32_e32 v179, v90
	v_exp_f32_e32 v182, v91
	v_exp_f32_e32 v154, v92
	v_exp_f32_e32 v155, v93
	v_exp_f32_e32 v156, v94
	v_exp_f32_e32 v180, v95
	v_pk_fma_f32 v[142:143], v[64:65], s[76:77], v[128:129] op_sel_hi:[1,0,0]
	v_add_f32_e32 v64, v175, v176
	s_add_u32 s10, s10, 0x10000
	v_fmac_f32_e32 v64, v173, v158
	v_add_f32_e32 v158, v183, v184
	s_addc_u32 s11, s11, 0
	s_add_i32 s14, s14, 2
	v_pk_fma_f32 v[140:141], v[66:67], s[76:77], v[128:129] op_sel_hi:[1,0,0]
	v_pk_fma_f32 v[136:137], v[68:69], s[76:77], v[128:129] op_sel_hi:[1,0,0]
	v_pk_fma_f32 v[132:133], v[70:71], s[76:77], v[128:129] op_sel_hi:[1,0,0]
	v_pk_fma_f32 v[130:131], v[72:73], s[76:77], v[128:129] op_sel_hi:[1,0,0]
	v_pk_fma_f32 v[138:139], v[74:75], s[76:77], v[128:129] op_sel_hi:[1,0,0]
	v_pk_fma_f32 v[134:135], v[76:77], s[76:77], v[128:129] op_sel_hi:[1,0,0]
	v_pk_fma_f32 v[128:129], v[78:79], s[76:77], v[128:129] op_sel_hi:[1,0,0]
	v_fmac_f32_e32 v158, v64, v177
	s_cmp_ge_u32 s14, s43
	s_waitcnt vmcnt(2)
	s_waitcnt lgkmcnt(0)
	s_barrier
	s_cbranch_scc1 .LBB0_934
	v_mov_b32_e32 v173, v144
	s_branch .LBB0_924
.LBB0_934:
	s_waitcnt vmcnt(0)
	ds_read_b128 v[64:67], v161 offset:49152
	ds_read_b128 v[68:71], v161 offset:57344
	s_waitcnt lgkmcnt(1)
	v_mfma_f32_32x32x16_bf16 v[80:95], v[64:67], v[112:115], 0
	s_waitcnt lgkmcnt(0)
	v_mfma_f32_32x32x16_bf16 v[64:79], v[68:71], v[112:115], 0
	ds_read_b128 v[112:115], v170 offset:49152
	ds_read_b128 v[162:165], v170 offset:57344
	s_waitcnt lgkmcnt(1)
	v_mfma_f32_32x32x16_bf16 v[80:95], v[112:115], v[108:111], v[80:95]
	s_waitcnt lgkmcnt(0)
	v_mfma_f32_32x32x16_bf16 v[64:79], v[162:165], v[108:111], v[64:79]
	ds_read_b128 v[108:111], v169 offset:49152
	ds_read_b128 v[112:115], v169 offset:57344
	s_waitcnt lgkmcnt(1)
	v_mfma_f32_32x32x16_bf16 v[80:95], v[108:111], v[120:123], v[80:95]
	s_waitcnt lgkmcnt(0)
	v_mfma_f32_32x32x16_bf16 v[64:79], v[112:115], v[120:123], v[64:79]
	ds_read_b128 v[108:111], v168 offset:49152
	ds_read_b128 v[112:115], v168 offset:57344
	v_exp_f32_e32 v120, v128
	v_exp_f32_e32 v121, v129
	s_waitcnt lgkmcnt(1)
	v_mfma_f32_32x32x16_bf16 v[80:95], v[108:111], v[124:127], v[80:95]
	s_waitcnt lgkmcnt(0)
	v_mfma_f32_32x32x16_bf16 v[64:79], v[112:115], v[124:127], v[64:79]
	ds_read_b128 v[108:111], v167 offset:49152
	ds_read_b128 v[112:115], v167 offset:57344
	s_waitcnt lgkmcnt(1)
	v_mfma_f32_32x32x16_bf16 v[80:95], v[108:111], v[116:119], v[80:95]
	s_waitcnt lgkmcnt(0)
	v_mfma_f32_32x32x16_bf16 v[64:79], v[112:115], v[116:119], v[64:79]
	ds_read_b128 v[108:111], v166 offset:49152
	ds_read_b128 v[112:115], v166 offset:57344
	v_exp_f32_e32 v116, v138
	v_exp_f32_e32 v117, v139
	v_exp_f32_e32 v118, v134
	v_exp_f32_e32 v119, v135
	s_waitcnt lgkmcnt(1)
	v_mfma_f32_32x32x16_bf16 v[80:95], v[108:111], v[104:107], v[80:95]
	s_waitcnt lgkmcnt(0)
; #define SBAR() __builtin_amdgcn_sched_barrier(0)
; #define RESC(a) do { if (__any((a) < 1.f)) { if (hi == 0) al_l[r32] = (a); asm volatile("s_waitcnt lgkmcnt(0)" ::: "memory"); \
;     _Pragma("unroll") for (int d = 0; d < 4; ++d) _Pragma("unroll") for (int r = 0; r < 16; ++r) o[d][r] *= al_l[crow(r, hi)]; } } while (0)
; template <int DK, int LDQ, int LDK, int LDV, int LDO, int SDEPTH, int NPARK>
; __device__ __forceinline__ void body(const bf16_t* __restrict__ Qb, const bf16_t* __restrict__ Kh, const bf16_t* __restrict__ Vh, bf16_t* __restrict__ Ob, int seq, char* lds, int tid, int wid) {
;     ...
;   SBAR(); qkt<DK, NPARK>(pB0, pB1, K_lds + SHM_K, qr, qpark, r32, hi);
;   finishSM(pA0, pA1, alA, l_reg, pa0, pa1, pa2, pa3); SBAR();
;   pv_d0(o, vb0, pa0, pa1, pa2, pa3); partialSM<DK>(pB0, pB1, m_reg, mnB, alB);
;   __syncthreads(); RESC(alB);
;   finishSM(pB0, pB1, alB, l_reg, pa0, pa1, pa2, pa3); SBAR();
	v_mfma_f32_32x32x16_bf16 v[64:79], v[112:115], v[104:107], v[64:79]
	ds_read_b128 v[104:107], v172 offset:49152
	ds_read_b128 v[108:111], v172 offset:57344
	v_exp_f32_e32 v112, v132
	v_exp_f32_e32 v113, v133
	v_exp_f32_e32 v114, v130
	v_exp_f32_e32 v115, v131
	s_waitcnt lgkmcnt(1)
	v_mfma_f32_32x32x16_bf16 v[80:95], v[104:107], v[100:103], v[80:95]
	s_waitcnt lgkmcnt(0)
	v_mfma_f32_32x32x16_bf16 v[64:79], v[108:111], v[100:103], v[64:79]
	ds_read_b128 v[100:103], v171 offset:49152
	ds_read_b128 v[104:107], v171 offset:57344
	v_exp_f32_e32 v108, v140
	v_exp_f32_e32 v109, v141
	v_exp_f32_e32 v110, v136
	v_exp_f32_e32 v111, v137
	s_waitcnt lgkmcnt(1)
	v_mfma_f32_32x32x16_bf16 v[80:95], v[100:103], v[96:99], v[80:95]
	s_waitcnt lgkmcnt(0)
	v_mfma_f32_32x32x16_bf16 v[64:79], v[104:107], v[96:99], v[64:79]
	v_add_f32_e32 v96, 0, v145
	v_add_f32_e32 v96, v187, v96
	v_add_f32_e32 v96, v146, v96
	v_add_f32_e32 v96, v188, v96
	v_add_f32_e32 v96, v186, v96
	v_add_f32_e32 v96, v189, v96
	v_add_f32_e32 v96, v147, v96
	v_add_f32_e32 v96, v185, v96
	v_add_f32_e32 v96, v157, v96
	v_add_f32_e32 v96, v181, v96
	v_add_f32_e32 v96, v179, v96
	v_add_f32_e32 v96, v182, v96
	v_exp_f32_e32 v106, v142
	v_add_f32_e32 v96, v154, v96
	v_exp_f32_e32 v107, v143
	v_add_f32_e32 v96, v155, v96
	v_add_f32_e32 v96, v156, v96
	v_add_f32_e32 v96, v180, v96
	v_add_f32_e32 v96, v106, v96
	v_add_f32_e32 v96, v107, v96
	v_add_f32_e32 v96, v108, v96
	v_add_f32_e32 v96, v109, v96
	v_add_f32_e32 v96, v110, v96
	v_add_f32_e32 v96, v111, v96
	v_add_f32_e32 v96, v112, v96
	v_add_f32_e32 v96, v113, v96
	v_add_f32_e32 v96, v114, v96
	v_add_f32_e32 v96, v115, v96
	v_add_f32_e32 v96, v116, v96
	v_add_f32_e32 v96, v117, v96
	v_add_f32_e32 v96, v118, v96
	v_add_f32_e32 v96, v119, v96
	v_add_f32_e32 v96, v120, v96
	v_add_f32_e32 v96, v121, v96
	v_mov_b32_e32 v97, v96
	v_cvt_pk_bf16_f32 v98, v145, v187
	v_cvt_pk_bf16_f32 v99, v146, v188
	v_cvt_pk_bf16_f32 v100, v186, v189
	v_cvt_pk_bf16_f32 v101, v147, v185
	s_nop 1
	v_permlane32_swap_b32_e32 v96, v97
	v_permlane32_swap_b32_e32 v98, v100
	v_permlane32_swap_b32_e32 v99, v101
	v_cvt_pk_bf16_f32 v102, v157, v181
	v_cvt_pk_bf16_f32 v103, v179, v182
	v_cvt_pk_bf16_f32 v104, v154, v155
	v_cvt_pk_bf16_f32 v105, v156, v180
	v_cvt_pk_bf16_f32 v106, v106, v107
	v_cvt_pk_bf16_f32 v107, v108, v109
	v_cvt_pk_bf16_f32 v108, v110, v111
	v_cvt_pk_bf16_f32 v109, v112, v113
	v_cvt_pk_bf16_f32 v110, v114, v115
	v_cvt_pk_bf16_f32 v111, v116, v117
	v_cvt_pk_bf16_f32 v112, v118, v119
	v_cvt_pk_bf16_f32 v113, v120, v121
	s_nop 0
	v_permlane32_swap_b32_e32 v102, v104
	v_permlane32_swap_b32_e32 v103, v105
	v_permlane32_swap_b32_e32 v106, v108
	v_permlane32_swap_b32_e32 v107, v109
	v_permlane32_swap_b32_e32 v110, v112
	v_permlane32_swap_b32_e32 v111, v113
	ds_read_b64_tr_b16 v[114:115], v160 offset:0
	ds_read_b64_tr_b16 v[116:117], v160 offset:0x800
	ds_read_b64_tr_b16 v[118:119], v160 offset:0x1000
	ds_read_b64_tr_b16 v[120:121], v160 offset:0x1800
	ds_read_b64_tr_b16 v[122:123], v160 offset:0x2000
	ds_read_b64_tr_b16 v[124:125], v160 offset:0x2800
	ds_read_b64_tr_b16 v[126:127], v160 offset:0x3000
	ds_read_b64_tr_b16 v[128:129], v160 offset:0x3800
	s_waitcnt lgkmcnt(0)
	s_nop 0
	v_mfma_f32_32x32x16_bf16 v[0:15], v[98:101], v[114:117], v[0:15]
	ds_read_b64_tr_b16 v[114:115], v160 offset:0x200
	ds_read_b64_tr_b16 v[116:117], v160 offset:0xa00
	v_mfma_f32_32x32x16_bf16 v[0:15], v[102:105], v[118:121], v[0:15]
	ds_read_b64_tr_b16 v[118:119], v160 offset:0x1200
	ds_read_b64_tr_b16 v[120:121], v160 offset:0x1a00
	v_mfma_f32_32x32x16_bf16 v[0:15], v[106:109], v[122:125], v[0:15]
	ds_read_b64_tr_b16 v[122:123], v160 offset:0x2200
	ds_read_b64_tr_b16 v[124:125], v160 offset:0x2a00
	v_mfma_f32_32x32x16_bf16 v[0:15], v[110:113], v[126:129], v[0:15]
	ds_read_b64_tr_b16 v[126:127], v160 offset:0x3200
	ds_read_b64_tr_b16 v[128:129], v160 offset:0x3a00
	s_waitcnt lgkmcnt(0)
	v_mfma_f32_32x32x16_bf16 v[48:63], v[98:101], v[114:117], v[48:63]
	ds_read_b64_tr_b16 v[114:115], v160 offset:0x400
	ds_read_b64_tr_b16 v[116:117], v160 offset:0xc00
	v_mfma_f32_32x32x16_bf16 v[48:63], v[102:105], v[118:121], v[48:63]
	ds_read_b64_tr_b16 v[118:119], v160 offset:0x1400
	ds_read_b64_tr_b16 v[120:121], v160 offset:0x1c00
	v_mfma_f32_32x32x16_bf16 v[48:63], v[106:109], v[122:125], v[48:63]
	ds_read_b64_tr_b16 v[122:123], v160 offset:0x2400
	ds_read_b64_tr_b16 v[124:125], v160 offset:0x2c00
	v_mfma_f32_32x32x16_bf16 v[48:63], v[110:113], v[126:129], v[48:63]
	ds_read_b64_tr_b16 v[126:127], v160 offset:0x3400
	ds_read_b64_tr_b16 v[128:129], v160 offset:0x3c00
	s_waitcnt lgkmcnt(0)
	v_mfma_f32_32x32x16_bf16 v[32:47], v[98:101], v[114:117], v[32:47]
	ds_read_b64_tr_b16 v[114:115], v160 offset:0x600
	ds_read_b64_tr_b16 v[116:117], v160 offset:0xe00
	v_mfma_f32_32x32x16_bf16 v[32:47], v[102:105], v[118:121], v[32:47]
	ds_read_b64_tr_b16 v[118:119], v160 offset:0x1600
	ds_read_b64_tr_b16 v[120:121], v160 offset:0x1e00
	v_mfma_f32_32x32x16_bf16 v[32:47], v[106:109], v[122:125], v[32:47]
	ds_read_b64_tr_b16 v[122:123], v160 offset:0x2600
	ds_read_b64_tr_b16 v[124:125], v160 offset:0x2e00
	v_mfma_f32_32x32x16_bf16 v[32:47], v[110:113], v[126:129], v[32:47]
	ds_read_b64_tr_b16 v[126:127], v160 offset:0x3600
	ds_read_b64_tr_b16 v[128:129], v160 offset:0x3e00
	s_waitcnt lgkmcnt(0)
	v_mfma_f32_32x32x16_bf16 v[16:31], v[98:101], v[114:117], v[16:31]
	v_max_f32_e32 v98, v81, v81
	v_max_f32_e32 v99, v80, v80
	v_max_f32_e32 v98, v99, v98
	v_max3_f32 v98, v98, v82, v83
	v_max3_f32 v98, v98, v84, v85
	v_max3_f32 v98, v98, v86, v87
	v_max3_f32 v98, v98, v88, v89
	v_max3_f32 v98, v98, v90, v91
	v_max3_f32 v98, v98, v92, v93
	v_mfma_f32_32x32x16_bf16 v[16:31], v[102:105], v[118:121], v[16:31]
	v_max3_f32 v98, v98, v94, v95
	v_max3_f32 v98, v98, v64, v65
	v_max3_f32 v98, v98, v66, v67
	v_max3_f32 v98, v98, v68, v69
	v_max3_f32 v98, v98, v70, v71
	v_max3_f32 v98, v98, v72, v73
	v_max3_f32 v98, v98, v74, v75
	v_max3_f32 v98, v98, v76, v77
	v_mfma_f32_32x32x16_bf16 v[16:31], v[106:109], v[122:125], v[16:31]
	v_max3_f32 v98, v98, v78, v79
	v_mov_b32_e32 v99, v98
	s_nop 1
	v_permlane32_swap_b32_e32 v98, v99
	v_max_f32_e32 v99, v99, v99
	v_max_f32_e32 v98, v98, v98
	v_max_f32_e32 v98, v98, v99
	v_sub_f32_e32 v99, v98, v174
	v_cmp_ge_f32_e32 vcc, s1, v99
	v_max_f32_e32 v99, v174, v174
	v_max_f32_e32 v99, v99, v98
	v_mfma_f32_32x32x16_bf16 v[16:31], v[110:113], v[126:129], v[16:31]
	v_sub_f32_e32 v98, v174, v99
	v_mul_f32_e32 v98, 0x3e0293ee, v98
	v_exp_f32_e32 v98, v98
	s_cmp_eq_u64 vcc, exec
	s_cselect_b64 s[8:9], -1, 0
	v_cndmask_b32_e64 v98, v98, 1.0, s[8:9]
	v_cmp_gt_f32_e32 vcc, 1.0, v98
	s_barrier
	s_cbranch_vccz .LBB0_938
	s_and_saveexec_b64 s[10:11], s[6:7]
	ds_write_b32 v151, v98 offset:128
	s_or_b64 exec, exec, s[10:11]
	s_waitcnt lgkmcnt(0)
	v_add_u32_e32 v112, s95, v150
	ds_read_b128 v[100:103], v112 offset:224
	ds_read_b128 v[104:107], v112 offset:192
	ds_read_b128 v[108:111], v112 offset:160
	ds_read_b128 v[112:115], v112 offset:128
	s_waitcnt lgkmcnt(3)
	v_pk_mul_f32 v[12:13], v[12:13], v[100:101]
	s_waitcnt lgkmcnt(2)
	v_pk_mul_f32 v[8:9], v[8:9], v[104:105]
	s_waitcnt lgkmcnt(1)
	v_pk_mul_f32 v[4:5], v[4:5], v[108:109]
	v_pk_mul_f32 v[14:15], v[14:15], v[102:103]
	v_pk_mul_f32 v[10:11], v[10:11], v[106:107]
	v_pk_mul_f32 v[6:7], v[6:7], v[110:111]
	s_waitcnt lgkmcnt(0)
	v_pk_mul_f32 v[2:3], v[2:3], v[114:115]
	v_pk_mul_f32 v[0:1], v[0:1], v[112:113]
	v_pk_mul_f32 v[60:61], v[60:61], v[100:101]
	v_pk_mul_f32 v[56:57], v[56:57], v[104:105]
	v_pk_mul_f32 v[52:53], v[52:53], v[108:109]
	v_pk_mul_f32 v[62:63], v[62:63], v[102:103]
	v_pk_mul_f32 v[58:59], v[58:59], v[106:107]
	v_pk_mul_f32 v[54:55], v[54:55], v[110:111]
	v_pk_mul_f32 v[50:51], v[50:51], v[114:115]
	v_pk_mul_f32 v[48:49], v[48:49], v[112:113]
	v_pk_mul_f32 v[44:45], v[44:45], v[100:101]
	v_pk_mul_f32 v[40:41], v[40:41], v[104:105]
	v_pk_mul_f32 v[36:37], v[36:37], v[108:109]
	v_pk_mul_f32 v[46:47], v[46:47], v[102:103]
	v_pk_mul_f32 v[42:43], v[42:43], v[106:107]
	v_pk_mul_f32 v[38:39], v[38:39], v[110:111]
	v_pk_mul_f32 v[34:35], v[34:35], v[114:115]
	v_pk_mul_f32 v[32:33], v[32:33], v[112:113]
	v_pk_mul_f32 v[28:29], v[28:29], v[100:101]
	v_pk_mul_f32 v[24:25], v[24:25], v[104:105]
	v_pk_mul_f32 v[20:21], v[20:21], v[108:109]
	v_pk_mul_f32 v[30:31], v[30:31], v[102:103]
	v_pk_mul_f32 v[26:27], v[26:27], v[106:107]
	v_pk_mul_f32 v[22:23], v[22:23], v[110:111]
	v_pk_mul_f32 v[18:19], v[18:19], v[114:115]
	v_pk_mul_f32 v[16:17], v[16:17], v[112:113]
